# stack1 + P4 items mapped to the panel's own team, P4|P5 seam = team barrier + cross-team Oloc/MRG guard (grid barrier fallback kept)
# speedup vs baseline: 1.0058x; 1.0058x over previous
; #define GAS __attribute__((address_space(1)))
; __device__ __forceinline__ void p4_load_a(P4Pre& P, const P4Ptr& p, int lane) {
;     const int r = lane & 15, g = lane >> 4, t = 16 * p.mt + r;
; #pragma unroll
;     for (int kb = 0; kb < 4; ++kb) P.ya[kb] = *(const GAS bf16x8*)(p.region + (size_t)((p.mt * 4 + kb) * 64 + lane) * 8);
; #pragma unroll
;     for (int vt = 0; vt < 4; ++vt)
; #pragma unroll
;         for (int kb = 0; kb < 4; ++kb) P.x[vt][kb] = *(const GAS bf16x8*)(p.sn + (size_t)((vt * 4 + kb) * 64 + lane) * 8);
; #pragma unroll
;     for (int vt = 0; vt < 8; ++vt) { P.ol[vt] = *(const GAS u64_t*)(p.oloc + (size_t)((vt * 4 + p.mt) * 64 + lane) * 4); P.gt8[vt] = *(const GAS u64_t*)(p.region + 24576 + t * 128 + 16 * vt + 4 * g); }
; __device__ __forceinline__ void p4_run(int gw, int NGW, const bf16_t* HGR, const bf16_t* DNR, const bf16_t* OLH, const bf16_t* OLD, const bf16_t* BNB, const float* hg_nw, const float* dn_nw, bf16_t* OAB, int lane) {
;     const int r = lane & 15, g = lane >> 4;
;     P4Pre P; P4Ptr p = p4_ptrs(gw, HGR, DNR, OLH, OLD, BNB, hg_nw, dn_nw);
;     if (gw < 8192) p4_load_a(P, p, lane);
.LBB0_890:
	s_add_u32 s10, s60, 0xa004000
	s_addc_u32 s11, s61, 0
	s_add_u32 s8, s60, 0xe000000
	s_addc_u32 s9, s61, 0
	s_cmp_lt_i32 s56, 5
	s_cselect_b64 s[0:1], -1, 0
	s_cmp_gt_i32 s57, 4
	s_cselect_b64 s[4:5], -1, 0
	s_and_b64 s[0:1], s[0:1], s[4:5]
	s_andn2_b64 vcc, exec, s[0:1]
	s_cbranch_vccnz .LBB0_946
	s_and_b32 s4, s72, 56
	s_and_b32 s0, s73, 7
	s_or_b32 s4, s4, s0
	s_lshl_b32 s4, s4, 6
	s_lshr_b32 s0, s2, 6
	s_lshl_b32 s0, s0, 3
	s_add_i32 s4, s4, s0
	s_add_i32 s4, s4, s48
	s_cmpk_gt_i32 s4, 0x1fff
	s_cbranch_scc1 .LBB0_896
	s_bfe_u32 s36, s4, 0xa0002
	s_bfe_u32 s48, s4, 0x20002
	s_lshl_b32 s3, s36, 16
	s_lshl_b32 s0, s48, 9
	s_add_u32 s0, s24, s0
	s_addc_u32 s1, s25, 0
	s_cmpk_lt_u32 s4, 0x1000
	s_cselect_b32 s7, s26, s62
	s_cselect_b32 s6, s27, s63
	s_cselect_b32 s1, s1, s31
	s_cselect_b32 s0, s0, s30
	s_add_u32 s28, s7, s3
	s_addc_u32 s29, s6, 0
	s_add_u32 s3, s28, 0x4000
	s_addc_u32 s7, s29, 0
	s_lshl_b32 s6, s36, 15
	s_add_u32 s6, s64, s6
	s_addc_u32 s18, s65, 0
	s_cmpk_lt_u32 s4, 0x1000
	s_cselect_b32 s6, s3, s6
	s_cselect_b32 s7, s7, s18
	s_add_u32 s3, s60, 0xf000000
	s_addc_u32 s33, s61, 0
	v_mov_b32_e32 v149, 0
	s_cmpk_lt_u32 s4, 0x1000
	s_waitcnt vmcnt(4)
	v_lshlrev_b32_e32 v26, 4, v234
	v_mov_b32_e32 v27, v149
	s_movk_i32 s5, 0x1000
	s_cselect_b32 s37, s8, s3
	s_cselect_b32 s39, s9, s33
	s_lshl_b32 s35, s34, 3
	v_lshlrev_b32_e32 v2, 11, v0
	s_lshr_b32 s42, s4, 2
	s_bfe_u32 s38, s66, 0x20006
	s_lshl_b32 s36, s36, 14
	s_waitcnt vmcnt(2)
	v_lshl_add_u64 v[42:43], s[6:7], 0, v[26:27]
	v_and_b32_e32 v148, 0x7800, v2
	v_lshlrev_b32_e32 v2, 7, v0
	s_add_u32 s36, s37, s36
	v_add_co_u32_e32 v44, vcc, s5, v42
	v_and_b32_e32 v2, 0x780, v2
	s_addc_u32 s37, s39, 0
	v_addc_co_u32_e32 v45, vcc, 0, v43, vcc
	s_movk_i32 s39, 0x2000
	v_lshrrev_b32_e32 v1, 2, v234
	v_lshl_or_b32 v82, s38, 11, v2
	v_add_co_u32_e32 v30, vcc, s39, v42
	v_and_b32_e32 v150, 12, v1
	v_lshl_add_u64 v[152:153], s[10:11], 0, v[148:149]
	v_lshlrev_b32_e32 v148, 1, v82
	v_addc_co_u32_e32 v31, vcc, 0, v43, vcc
	s_movk_i32 s40, 0x3000
	v_lshl_add_u64 v[2:3], s[28:29], 0, v[148:149]
	v_lshlrev_b32_e32 v148, 1, v150
	v_add_co_u32_e32 v42, vcc, s40, v42
	v_lshlrev_b32_e32 v146, 3, v234
	v_lshl_add_u64 v[84:85], v[2:3], 0, v[148:149]
	s_mov_b64 s[18:19], 0xc000
	v_addc_co_u32_e32 v43, vcc, 0, v43, vcc
	s_mov_b32 s41, 0xc000
	v_lshl_add_u64 v[86:87], v[84:85], 0, s[18:19]
	v_lshl_or_b32 v154, s38, 9, v146
	v_mov_b32_e32 v155, v149
	v_add_co_u32_e32 v84, vcc, s41, v84
	v_lshl_add_u64 v[88:89], s[36:37], 0, v[154:155]
	v_lshl_or_b32 v156, s38, 12, v26
	v_addc_co_u32_e32 v85, vcc, 0, v85, vcc
	global_load_dwordx4 v[2:5], v156, s[28:29]
	global_load_dwordx4 v[6:9], v156, s[28:29] offset:1024
	global_load_dwordx4 v[10:13], v156, s[28:29] offset:2048
	global_load_dwordx4 v[14:17], v156, s[28:29] offset:3072
	global_load_dwordx4 v[18:21], v26, s[6:7]
	global_load_dwordx4 v[22:25], v26, s[6:7] offset:1024
	global_load_dwordx4 v[38:41], v26, s[6:7] offset:2048
	global_load_dwordx4 v[50:53], v26, s[6:7] offset:3072
	global_load_dwordx4 v[34:37], v[44:45], off offset:1024
	global_load_dwordx4 v[46:49], v[44:45], off offset:2048
	s_nop 0
	global_load_dwordx4 v[26:29], v[30:31], off offset:-4096
	global_load_dwordx4 v[54:57], v[30:31], off
	global_load_dwordx4 v[58:61], v[30:31], off offset:1024
	global_load_dwordx4 v[66:69], v[30:31], off offset:2048
	s_nop 0
	global_load_dwordx4 v[30:33], v[30:31], off offset:3072
	s_nop 0
	global_load_dwordx4 v[78:81], v[44:45], off offset:3072
	global_load_dwordx4 v[74:77], v[42:43], off
	global_load_dwordx4 v[70:73], v[42:43], off offset:1024
	global_load_dwordx4 v[62:65], v[42:43], off offset:2048
	s_nop 0
	global_load_dwordx4 v[42:45], v[42:43], off offset:3072
	s_nop 0
	global_load_dwordx2 v[210:211], v[84:85], off
	global_load_dwordx2 v[166:167], v154, s[36:37]
	global_load_dwordx2 v[168:169], v154, s[36:37] offset:2048
	v_add_co_u32_e32 v84, vcc, s5, v88
	s_ashr_i32 s51, s4, 12
	s_nop 0
	v_addc_co_u32_e32 v85, vcc, 0, v89, vcc
	v_add_co_u32_e32 v90, vcc, s39, v88
	s_bfe_u32 s28, s42, 0x80002
	s_nop 0
	v_addc_co_u32_e32 v91, vcc, 0, v89, vcc
	global_load_dwordx2 v[208:209], v[86:87], off offset:32
	global_load_dwordx2 v[204:205], v[86:87], off offset:64
	global_load_dwordx2 v[198:199], v[86:87], off offset:96
	global_load_dwordx2 v[180:181], v[86:87], off offset:128
	global_load_dwordx2 v[174:175], v[90:91], off offset:-4096
	global_load_dwordx2 v[176:177], v[90:91], off
	global_load_dwordx2 v[178:179], v[90:91], off offset:2048
	global_load_dwordx2 v[172:173], v[86:87], off offset:160
	global_load_dwordx2 v[170:171], v[86:87], off offset:192
	global_load_dwordx2 v[164:165], v[86:87], off offset:224
	v_add_co_u32_e32 v86, vcc, s40, v88
	s_mov_b32 s29, 0
	s_nop 0
	v_addc_co_u32_e32 v87, vcc, 0, v89, vcc
	global_load_dwordx2 v[184:185], v[84:85], off offset:2048
	global_load_dwordx2 v[186:187], v[86:87], off
	global_load_dwordx2 v[188:189], v[86:87], off offset:2048
	v_and_b32_e32 v84, 16, v0
	v_and_b32_e32 v86, 8, v1
	v_mbcnt_lo_u32_b32 v1, -1, 0
	v_mov_b32_e32 v157, v149
	s_movk_i32 s42, 0x4000
	s_movk_i32 s43, 0x5000
	s_movk_i32 s44, 0x6000
	s_movk_i32 s45, 0x7000
	v_lshlrev_b32_e32 v158, 1, v82
	v_lshlrev_b32_e32 v160, 1, v84
	v_lshlrev_b32_e32 v162, 1, v86
	v_mbcnt_hi_u32_b32 v1, -1, v1
	v_mov_b32_e32 v147, 0x358637bd
	s_mov_b32 s46, 0x800000
	s_mov_b32 s49, s51
	s_mov_b32 s50, s28
	s_mov_b32 s47, s48
	s_waitcnt vmcnt(15)
	v_mov_b64_e32 v[182:183], v[210:211]
	s_waitcnt vmcnt(12)
	v_mov_b64_e32 v[190:191], v[208:209]
	s_waitcnt vmcnt(11)
	v_mov_b64_e32 v[192:193], v[204:205]
	s_waitcnt vmcnt(10)
	v_mov_b64_e32 v[194:195], v[198:199]
	s_waitcnt vmcnt(9)
	v_mov_b64_e32 v[196:197], v[180:181]
	s_waitcnt vmcnt(5)
	v_mov_b64_e32 v[200:201], v[172:173]
	s_waitcnt vmcnt(4)
	v_mov_b64_e32 v[202:203], v[170:171]
	s_waitcnt vmcnt(3)
	v_mov_b64_e32 v[206:207], v[164:165]
	s_branch .LBB0_894

; #define GAS __attribute__((address_space(1)))
; #define MFMA16(a, b, c) __builtin_amdgcn_mfma_f32_16x16x32_bf16((a), (b), (c), 0, 0, 0)
; __device__ __forceinline__ void p4_run(int gw, int NGW, const bf16_t* HGR, const bf16_t* DNR, const bf16_t* OLH, const bf16_t* OLD, const bf16_t* BNB, const float* hg_nw, const float* dn_nw, bf16_t* OAB, int lane) {
;     ...
;     for (int it = gw; it < 8192; it += NGW) {
;         asm volatile("" ::: "memory");
;         f32x4 o[8]; float ss = 0.f; u64_t gcur[8];
; #pragma unroll
;         for (int vt = 0; vt < 8; ++vt) gcur[vt] = P.gt8[vt];
; #pragma unroll
;         for (int vt = 0; vt < 4; ++vt) { f32x4 acc = unpack4(P.ol[vt]);
; #pragma unroll
;             for (int kb = 0; kb < 4; ++kb) acc = MFMA16(P.x[vt][kb], P.ya[kb], acc);
;             o[vt] = acc; ss += (acc[0] * acc[0] + acc[1] * acc[1]) + (acc[2] * acc[2] + acc[3] * acc[3]); }
;         asm volatile("" ::: "memory");
; #pragma unroll
;         for (int vt = 0; vt < 4; ++vt)
; #pragma unroll
;             for (int kb = 0; kb < 4; ++kb) P.x[vt][kb] = *(const GAS bf16x8*)(p.sn + (size_t)(((vt + 4) * 4 + kb) * 64 + lane) * 8);
;         f32x4 w8[8];
; #pragma unroll
;         for (int vt = 0; vt < 8; ++vt) w8[vt] = *(const GAS f32x4*)(p.nw + 16 * vt + 4 * g);
;         asm volatile("" ::: "memory");
; #pragma unroll
;         for (int vt = 0; vt < 4; ++vt) { f32x4 acc = unpack4(P.ol[vt + 4]);
; #pragma unroll
;             for (int kb = 0; kb < 4; ++kb) acc = MFMA16(P.x[vt][kb], P.ya[kb], acc);
;             o[vt + 4] = acc; ss += (acc[0] * acc[0] + acc[1] * acc[1]) + (acc[2] * acc[2] + acc[3] * acc[3]); }
;         const int t = 16 * p.mt + r;
;         bf16_t* orow2 = OAB + (size_t)(p.rb * 4 + p.mt) * 32768 + r * 1024 + p.br * 512 + p.h * 128 + 16 * (g & 1) + 8 * (g >> 1);
;         asm volatile("" :: "v"(o[4][0]), "v"(o[5][0]), "v"(o[6][0]), "v"(o[7][0]) : "memory");
;         if (it + NGW < 8192) { p = p4_ptrs(it + NGW, HGR, DNR, OLH, OLD, BNB, hg_nw, dn_nw); p4_load_a(P, p, lane); }
.LBB0_894:
	s_nop 0
	v_lshlrev_b32_e32 v82, 16, v166
	v_and_b32_e32 v83, 0xffff0000, v166
	v_lshlrev_b32_e32 v84, 16, v167
	v_and_b32_e32 v85, 0xffff0000, v167
	v_lshlrev_b32_e32 v148, 1, v146
	s_waitcnt vmcnt(0)
	v_lshlrev_b32_e32 v98, 16, v188
	v_mfma_f32_16x16x32_bf16 v[18:21], v[18:21], v[2:5], v[82:85]
	v_and_b32_e32 v99, 0xffff0000, v188
	v_lshlrev_b32_e32 v100, 16, v189
	v_and_b32_e32 v101, 0xffff0000, v189
	v_mfma_f32_16x16x32_bf16 v[18:21], v[22:25], v[6:9], v[18:21]
	v_lshlrev_b32_e32 v22, 16, v174
	v_and_b32_e32 v23, 0xffff0000, v174
	v_lshlrev_b32_e32 v24, 16, v175
	v_mfma_f32_16x16x32_bf16 v[18:21], v[38:41], v[10:13], v[18:21]
	v_and_b32_e32 v25, 0xffff0000, v175
	v_lshlrev_b32_e32 v151, 2, v150
	s_bitcmp1_b32 s4, 5
	s_cselect_b32 s35, 0xfe0, 32
	s_add_i32 s4, s4, s35
	v_mfma_f32_16x16x32_bf16 v[86:89], v[50:53], v[14:17], v[18:21]
	s_cmpk_gt_i32 s4, 0x1fff
	s_cselect_b64 s[36:37], -1, 0
	s_nop 1
	v_lshlrev_b32_e32 v18, 16, v168
	v_and_b32_e32 v19, 0xffff0000, v168
	v_lshlrev_b32_e32 v20, 16, v169
	v_and_b32_e32 v21, 0xffff0000, v169
	s_nop 1
	v_mfma_f32_16x16x32_bf16 v[18:21], v[26:29], v[2:5], v[18:21]
	v_mfma_f32_16x16x32_bf16 v[18:21], v[34:37], v[6:9], v[18:21]
	v_mfma_f32_16x16x32_bf16 v[18:21], v[46:49], v[10:13], v[18:21]
	v_lshlrev_b32_e32 v46, 16, v176
	v_and_b32_e32 v47, 0xffff0000, v176
	v_lshlrev_b32_e32 v48, 16, v177
	v_mfma_f32_16x16x32_bf16 v[82:85], v[78:81], v[14:17], v[18:21]
	v_and_b32_e32 v49, 0xffff0000, v177
	v_mfma_f32_16x16x32_bf16 v[18:21], v[54:57], v[2:5], v[22:25]
	v_mfma_f32_16x16x32_bf16 v[18:21], v[58:61], v[6:9], v[18:21]
	s_nop 1
	v_lshlrev_b32_e32 v22, 16, v184
	v_and_b32_e32 v23, 0xffff0000, v184
	v_lshlrev_b32_e32 v24, 16, v185
	v_and_b32_e32 v25, 0xffff0000, v185
	v_mfma_f32_16x16x32_bf16 v[34:37], v[66:69], v[10:13], v[18:21]
	v_lshl_add_u64 v[58:59], s[6:7], 0, v[148:149]
	v_add_co_u32_e32 v50, vcc, s43, v58
	v_mfma_f32_16x16x32_bf16 v[18:21], v[74:77], v[2:5], v[22:25]
	s_nop 0
	v_addc_co_u32_e32 v51, vcc, 0, v59, vcc
	v_add_co_u32_e32 v52, vcc, s42, v58
	v_mfma_f32_16x16x32_bf16 v[22:25], v[70:73], v[6:9], v[18:21]
	s_nop 3
	global_load_dwordx4 v[18:21], v[50:51], off offset:-4096
	global_load_dwordx4 v[26:29], v[50:51], off
	v_addc_co_u32_e32 v53, vcc, 0, v59, vcc
	v_mfma_f32_16x16x32_bf16 v[38:41], v[62:65], v[10:13], v[22:25]
	v_add_co_u32_e32 v94, vcc, s45, v58
	v_lshlrev_b32_e32 v62, 16, v186
	v_mfma_f32_16x16x32_bf16 v[114:117], v[30:33], v[14:17], v[34:37]
	global_load_dwordx4 v[22:25], v[52:53], off offset:1024
	v_addc_co_u32_e32 v95, vcc, 0, v59, vcc
	s_nop 0
	global_load_dwordx4 v[34:37], v[50:51], off offset:1024
	v_mfma_f32_16x16x32_bf16 v[110:113], v[42:45], v[14:17], v[38:41]
	global_load_dwordx4 v[54:57], v[94:95], off offset:-4096
	v_add_co_u32_e32 v74, vcc, s44, v58
	s_nop 0
	global_load_dwordx4 v[38:41], v[52:53], off offset:2048
	v_addc_co_u32_e32 v75, vcc, 0, v59, vcc
	v_lshlrev_b32_e32 v30, 16, v178
	v_and_b32_e32 v31, 0xffff0000, v178
	v_lshlrev_b32_e32 v32, 16, v179
	v_and_b32_e32 v33, 0xffff0000, v179
	v_and_b32_e32 v63, 0xffff0000, v186
	v_lshlrev_b32_e32 v64, 16, v187
	v_and_b32_e32 v65, 0xffff0000, v187
	s_and_b64 vcc, exec, s[36:37]
	s_waitcnt vmcnt(5)
	v_mfma_f32_16x16x32_bf16 v[42:45], v[18:21], v[2:5], v[46:49]
	s_nop 2
	global_load_dwordx4 v[46:49], v[50:51], off offset:2048
	global_load_dwordx4 v[78:81], v[50:51], off offset:3072
	s_nop 0
	global_load_dwordx4 v[50:53], v[52:53], off offset:3072
	s_nop 0
	global_load_dwordx4 v[58:61], v[74:75], off offset:1024
	global_load_dwordx4 v[66:69], v[74:75], off offset:2048
	s_waitcnt vmcnt(9)
	v_mfma_f32_16x16x32_bf16 v[30:33], v[26:29], v[2:5], v[30:33]
	s_waitcnt vmcnt(7)
	v_mfma_f32_16x16x32_bf16 v[30:33], v[34:37], v[6:9], v[30:33]
	v_mfma_f32_16x16x32_bf16 v[42:45], v[22:25], v[6:9], v[42:45]
	s_waitcnt vmcnt(5)
	v_mfma_f32_16x16x32_bf16 v[42:45], v[38:41], v[10:13], v[42:45]
	v_mfma_f32_16x16x32_bf16 v[62:65], v[54:57], v[2:5], v[62:65]
	s_waitcnt vmcnt(2)
	v_mfma_f32_16x16x32_bf16 v[118:121], v[50:53], v[14:17], v[42:45]
	v_mfma_f32_16x16x32_bf16 v[70:73], v[46:49], v[10:13], v[30:33]
	s_nop 2
	global_load_dwordx4 v[30:33], v[74:75], off offset:3072
	v_mfma_f32_16x16x32_bf16 v[106:109], v[78:81], v[14:17], v[70:73]
	s_nop 2
	global_load_dwordx4 v[70:73], v[94:95], off offset:1024
	global_load_dwordx4 v[74:77], v[94:95], off
	s_waitcnt vmcnt(4)
	v_mfma_f32_16x16x32_bf16 v[42:45], v[58:61], v[6:9], v[62:65]
	s_nop 2
	global_load_dwordx4 v[62:65], v[94:95], off offset:2048
	s_waitcnt vmcnt(4)
	v_mfma_f32_16x16x32_bf16 v[90:93], v[66:69], v[10:13], v[42:45]
	s_nop 2
	global_load_dwordx4 v[42:45], v[94:95], off offset:3072
	global_load_dwordx4 v[142:145], v151, s[0:1]
	global_load_dwordx4 v[138:141], v151, s[0:1] offset:64
	global_load_dwordx4 v[134:137], v151, s[0:1] offset:128
	global_load_dwordx4 v[130:133], v151, s[0:1] offset:192
	global_load_dwordx4 v[126:129], v151, s[0:1] offset:256
	global_load_dwordx4 v[122:125], v151, s[0:1] offset:320
	s_waitcnt vmcnt(10)
	v_mfma_f32_16x16x32_bf16 v[94:97], v[30:33], v[14:17], v[90:93]
	s_waitcnt vmcnt(8)
	v_mfma_f32_16x16x32_bf16 v[90:93], v[74:77], v[2:5], v[98:101]
	v_mfma_f32_16x16x32_bf16 v[90:93], v[70:73], v[6:9], v[90:93]
	s_waitcnt vmcnt(7)
	v_mfma_f32_16x16x32_bf16 v[98:101], v[62:65], v[10:13], v[90:93]
	global_load_dwordx4 v[102:105], v151, s[0:1] offset:384
	s_nop 4
	global_load_dwordx4 v[90:93], v151, s[0:1] offset:448
	s_waitcnt vmcnt(8)
	v_mfma_f32_16x16x32_bf16 v[98:101], v[42:45], v[14:17], v[98:101]
	s_cbranch_vccnz .LBB0_893
; #define GAS __attribute__((address_space(1)))
; #define BOTH(k) (IN(k) && (k) + 1 < hi)
; #define GRID_BAR() xcd_barrier(bar)
; __device__ __forceinline__ void p4_load_a(P4Pre& P, const P4Ptr& p, int lane) {
;     const int r = lane & 15, g = lane >> 4, t = 16 * p.mt + r;
; #pragma unroll
;     for (int kb = 0; kb < 4; ++kb) P.ya[kb] = *(const GAS bf16x8*)(p.region + (size_t)((p.mt * 4 + kb) * 64 + lane) * 8);
; #pragma unroll
;     for (int vt = 0; vt < 4; ++vt)
; #pragma unroll
;         for (int kb = 0; kb < 4; ++kb) P.x[vt][kb] = *(const GAS bf16x8*)(p.sn + (size_t)((vt * 4 + kb) * 64 + lane) * 8);
; #pragma unroll
;     for (int vt = 0; vt < 8; ++vt) { P.ol[vt] = *(const GAS u64_t*)(p.oloc + (size_t)((vt * 4 + p.mt) * 64 + lane) * 4); P.gt8[vt] = *(const GAS u64_t*)(p.region + 24576 + t * 128 + 16 * vt + 4 * g); }
; __global__ void __launch_bounds__(NWAVES * 64, 2) fwd(Args args) {
;     ...
;         p4_run(gw, NGW, HGR, DNR, OLH, OLD, BNB, args.in[4], args.in[7], OAB, lane);
;         }
;         if (BOTH(4)) GRID_BAR();
	s_bfe_u32 s49, s4, 0xa0002
	s_bfe_u32 s47, s4, 0x20002
	s_lshl_b32 s6, s49, 16
	s_lshl_b32 s0, s47, 9
	s_add_u32 s0, s24, s0
	s_addc_u32 s1, s25, 0
	s_cmpk_lt_u32 s4, 0x1000
	s_cselect_b32 s50, s26, s62
	s_cselect_b32 s7, s27, s63
	s_cselect_b32 s1, s1, s31
	s_cselect_b32 s0, s0, s30
	s_add_u32 s66, s50, s6
	s_addc_u32 s67, s7, 0
	s_lshl_b32 s6, s49, 15
	s_add_u32 s6, s64, s6
	s_addc_u32 s7, s65, 0
	s_add_u32 s50, s66, 0x4000
	s_addc_u32 s68, s67, 0
	s_cmpk_lt_u32 s4, 0x1000
	s_cselect_b32 s6, s50, s6
	s_cselect_b32 s7, s68, s7
	v_lshl_add_u64 v[42:43], s[6:7], 0, v[148:149]
	v_add_co_u32_e32 v44, vcc, s5, v42
	v_lshl_add_u64 v[14:15], s[66:67], 0, v[156:157]
	s_nop 0
	v_addc_co_u32_e32 v45, vcc, 0, v43, vcc
	v_add_co_u32_e32 v30, vcc, s39, v42
	v_mov_b32_e32 v159, v149
	s_nop 0
	v_addc_co_u32_e32 v31, vcc, 0, v43, vcc
	s_cselect_b32 s69, s9, s33
	s_cselect_b32 s70, s8, s3
	s_lshr_b32 s50, s4, 2
	s_lshl_b32 s49, s49, 14
	global_load_dwordx4 v[2:5], v[14:15], off
	global_load_dwordx4 v[6:9], v[14:15], off offset:1024
	global_load_dwordx4 v[10:13], v[14:15], off offset:2048
	s_nop 0
	global_load_dwordx4 v[14:17], v[14:15], off offset:3072
	s_nop 0
	global_load_dwordx4 v[18:21], v148, s[6:7]
	global_load_dwordx4 v[22:25], v148, s[6:7] offset:1024
	global_load_dwordx4 v[38:41], v148, s[6:7] offset:2048
	global_load_dwordx4 v[50:53], v148, s[6:7] offset:3072
	v_add_co_u32_e32 v42, vcc, s40, v42
	v_lshl_add_u64 v[166:167], s[66:67], 0, v[158:159]
	v_lshlrev_b32_e32 v148, 1, v150
	s_add_u32 s68, s70, s49
	v_addc_co_u32_e32 v43, vcc, 0, v43, vcc
	v_lshl_add_u64 v[166:167], v[166:167], 0, v[148:149]
	s_addc_u32 s69, s69, 0
	v_lshl_add_u64 v[206:207], v[166:167], 0, s[18:19]
	v_add_co_u32_e32 v166, vcc, s41, v166
	v_lshl_add_u64 v[186:187], s[68:69], 0, v[154:155]
	s_nop 0
	v_addc_co_u32_e32 v167, vcc, 0, v167, vcc
	v_add_co_u32_e32 v176, vcc, s5, v186
	global_load_dwordx4 v[34:37], v[44:45], off offset:1024
	global_load_dwordx4 v[46:49], v[44:45], off offset:2048
	global_load_dwordx4 v[26:29], v[30:31], off offset:-4096
	global_load_dwordx4 v[54:57], v[30:31], off
	global_load_dwordx4 v[58:61], v[30:31], off offset:1024
	global_load_dwordx4 v[66:69], v[30:31], off offset:2048
	s_nop 0
	global_load_dwordx4 v[30:33], v[30:31], off offset:3072
	v_addc_co_u32_e32 v177, vcc, 0, v187, vcc
	v_add_co_u32_e32 v178, vcc, 0x2000, v186
	global_load_dwordx4 v[78:81], v[44:45], off offset:3072
	global_load_dwordx4 v[74:77], v[42:43], off
	global_load_dwordx4 v[70:73], v[42:43], off offset:1024
	global_load_dwordx4 v[62:65], v[42:43], off offset:2048
	s_nop 0
	global_load_dwordx4 v[42:45], v[42:43], off offset:3072
	v_addc_co_u32_e32 v179, vcc, 0, v187, vcc
	global_load_dwordx2 v[182:183], v[166:167], off
	s_nop 0
	global_load_dwordx2 v[166:167], v[186:187], off
	global_load_dwordx2 v[168:169], v[186:187], off offset:2048
	global_load_dwordx2 v[190:191], v[206:207], off offset:32
	global_load_dwordx2 v[192:193], v[206:207], off offset:64
	global_load_dwordx2 v[194:195], v[206:207], off offset:96
	global_load_dwordx2 v[196:197], v[206:207], off offset:128
	global_load_dwordx2 v[174:175], v[176:177], off
	global_load_dwordx2 v[184:185], v[176:177], off offset:2048
	s_nop 0
	global_load_dwordx2 v[176:177], v[178:179], off
	s_nop 0
	global_load_dwordx2 v[178:179], v[178:179], off offset:2048
	v_add_co_u32_e32 v188, vcc, 0x3000, v186
	s_ashr_i32 s49, s4, 12
	s_nop 0
	v_addc_co_u32_e32 v189, vcc, 0, v187, vcc
	global_load_dwordx2 v[186:187], v[188:189], off
	s_nop 0
	global_load_dwordx2 v[188:189], v[188:189], off offset:2048
	s_nop 0
	global_load_dwordx2 v[200:201], v[206:207], off offset:160
	global_load_dwordx2 v[202:203], v[206:207], off offset:192
	s_nop 0
	global_load_dwordx2 v[206:207], v[206:207], off offset:224
	s_bfe_u32 s50, s50, 0x80002
	s_branch .LBB0_893
.LBB0_896:
	s_cmp_lt_i32 s57, 6
	s_cbranch_scc1 .LBB0_946
	s_waitcnt vmcnt(0)
	s_barrier
	v_mov_b32_e32 v1, 0x22968
	ds_read_b32 v1, v1
	s_waitcnt lgkmcnt(0)
	v_readfirstlane_b32 s98, v1
	s_cmp_eq_u32 s98, 0
	s_cbranch_scc1 .Lp4_grid
	s_and_saveexec_b64 s[0:1], s[96:97]
	s_cbranch_execz .LBB0_945
	s_and_b32 s98, s72, 56
	s_and_b32 s99, s73, 7
	s_or_b32 s98, s98, s99
	s_lshl_b32 s99, s98, 7
	s_add_u32 s6, s60, s99
	s_addc_u32 s7, s61, 0
	s_add_u32 s6, s6, 0x26000
	s_addc_u32 s7, s7, 0
	s_and_b32 s99, s98, 31
	s_lshl_b32 s99, s99, 8
	s_add_u32 s4, s60, s99
	s_addc_u32 s5, s61, 0
	s_add_u32 s4, s4, 0x26000
	s_addc_u32 s5, s5, 0
	v_mov_b32_e32 v1, 0
	v_mov_b32_e32 v2, 1
	v_mov_b32_e32 v5, 0
	s_waitcnt vmcnt(0) lgkmcnt(0)
	global_atomic_add v1, v2, s[6:7]
	buffer_inv sc1
.Lp4_spin:
	global_load_dword v2, v1, s[6:7] sc1
	global_load_dword v3, v1, s[4:5] sc1
	global_load_dword v4, v1, s[4:5] offset:128 sc1
	s_waitcnt vmcnt(0)
	v_min_u32_e32 v2, v2, v3
	v_min_u32_e32 v2, v2, v4
	v_cmp_lt_u32_e32 vcc, 3, v2
	s_cbranch_vccnz .Lp4_done
	s_sleep 1
	v_add_u32_e32 v5, 1, v5
	v_cmp_gt_u32_e32 vcc, 0x4000, v5
	s_cbranch_vccnz .Lp4_spin
	v_mov_b32_e32 v2, 1
	global_atomic_add v1, v2, s[58:59] offset:512
.Lp4_done:
	s_waitcnt vmcnt(0)
	s_branch .LBB0_945
.Lp4_grid:
	s_and_saveexec_b64 s[0:1], s[96:97]
	s_cbranch_execz .LBB0_945
	s_add_i32 s3, 0, 0x22960
	v_mov_b32_e32 v1, s3
	s_waitcnt vmcnt(0) expcnt(0) lgkmcnt(0)
	ds_read_b32 v3, v1
	s_add_i32 s3, 0, 0x22964
	v_mov_b32_e32 v1, s3
	ds_read_b32 v1, v1
	s_waitcnt lgkmcnt(1)
	v_cmp_ne_u32_e32 vcc, 0, v3
	s_cbranch_vccnz .LBB0_913
	v_readlane_b32 s6, v240, 0
	v_readlane_b32 s7, v240, 1
	s_load_dwordx2 s[4:5], s[6:7], 0x4
	s_add_u32 s6, s58, 0x1000
	s_addc_u32 s7, s59, 0
	s_add_u32 s18, s58, 0x1100
	s_addc_u32 s19, s59, 0
	s_add_u32 s24, s58, 0x1200
	s_addc_u32 s25, s59, 0
	s_waitcnt lgkmcnt(0)
	s_mul_i32 s3, s4, s34
	s_add_u32 s28, s58, 0x1300
	s_mul_i32 s3, s3, s5
	s_addc_u32 s29, s59, 0
	s_mov_b32 s4, 1
	v_mov_b32_e32 v17, 0
	s_branch .LBB0_901
